# v17: v16 plus early L2 write-back by each XCD's first barrier arriver
# speedup vs baseline: 1.0106x; 1.0029x over previous
; DI unsigned xb_ld(unsigned* p)              { return __hip_atomic_load(p, __ATOMIC_RELAXED, __HIP_MEMORY_SCOPE_AGENT); }
; DI unsigned xb_add(unsigned* p, unsigned v) { return __hip_atomic_fetch_add(p, v, __ATOMIC_RELAXED, __HIP_MEMORY_SCOPE_AGENT); }
; #define XB_SPIN(cond, bar) do { unsigned _sp = 0; while (cond) { __builtin_amdgcn_s_sleep(1); \
;     if ((++_sp & 255u) == 0u) { if (xb_ld(&(bar)[XB_TMO])) break; if (_sp > XB_SPIN_CAP) { atomicAdd(&(bar)[XB_TMO], 1u); break; } } } } while (0)
; DI void xcd_barrier(const XcdBarrier& b, int wid) {
;     ...
;         unsigned nloc = b.st[0], nx = b.st[1];
;         if (nloc == 0u) { xcd_barrier_complete(bar, b.x, nloc, nx); b.st[0] = nloc; b.st[1] = nx; }
;         const unsigned old = xb_add(&bar[XB_XSUB(b.x)], 1u);
;         const unsigned gen = old / nloc;
;         if (old + 1u == (gen + 1u) * nloc) {
;             __builtin_amdgcn_fence(__ATOMIC_RELEASE, "agent");
;             asm volatile("s_waitcnt vmcnt(0)" ::: "memory");
;             const unsigned og = xb_add(&bar[XB_TOP], 1u);
;             const unsigned tg = og / nx;
;             if (og + 1u == (tg + 1u) * nx) xb_add(&bar[XB_TOPGEN], 1u);
;             else XB_SPIN(xb_ld(&bar[XB_TOPGEN]) == tg, bar);
;             __builtin_amdgcn_fence(__ATOMIC_ACQUIRE, "agent");
;             xb_add(&bar[XB_XGEN(b.x)], 1u);
;             asm volatile("s_waitcnt vmcnt(0)" ::: "memory");
;         } else {
;             XB_SPIN(xb_ld(&bar[XB_XGEN(b.x)]) == gen, bar);
.LBB0_1801:
	s_or_b64 exec, exec, s[2:3]
	v_cvt_f32_u32_e32 v4, v2
	s_waitcnt vmcnt(0)
	v_readfirstlane_b32 s2, v3
	v_sub_u32_e32 v3, 0, v2
	v_rcp_iflag_f32_e32 v4, v4
	v_add_u32_e32 v5, s2, v1
	v_mul_f32_e32 v4, 0x4f7ffffe, v4
	v_cvt_u32_f32_e32 v4, v4
	v_mul_lo_u32 v1, v3, v4
	v_mul_hi_u32 v1, v4, v1
	v_add_u32_e32 v1, v4, v1
	v_mul_hi_u32 v1, v5, v1
	v_mul_lo_u32 v3, v1, v2
	v_sub_u32_e32 v3, v5, v3
	v_add_u32_e32 v4, 1, v1
	v_cmp_ge_u32_e32 vcc, v3, v2
	s_nop 1
	v_cndmask_b32_e32 v1, v1, v4, vcc
	v_sub_u32_e32 v4, v3, v2
	v_cndmask_b32_e32 v3, v3, v4, vcc
	v_add_u32_e32 v4, 1, v1
	v_cmp_ge_u32_e32 vcc, v3, v2
	v_add_u32_e32 v3, 1, v5
	s_nop 0
	v_cndmask_b32_e32 v1, v1, v4, vcc
	v_mul_lo_u32 v4, v2, v1
	v_add_u32_e32 v2, v4, v2
	v_cmp_ne_u32_e32 vcc, v3, v2
	s_and_saveexec_b64 s[2:3], vcc
	s_xor_b64 s[2:3], exec, s[2:3]
	s_cbranch_execz .LBB0_1815
	v_cmp_eq_u32_e32 vcc, v5, v4
	s_cbranch_vccz .Lxb_noearly_0
	buffer_wbl2 sc1
.Lxb_noearly_0:
	v_readlane_b32 s4, v255, 4
	v_readlane_b32 s5, v255, 5
	s_waitcnt lgkmcnt(0)
	s_nop 3
	global_load_dword v0, v97, s[4:5] sc1
	s_waitcnt vmcnt(0)
	v_cmp_eq_u32_e32 vcc, v0, v1
	s_and_saveexec_b64 s[4:5], vcc
	s_cbranch_execz .LBB0_1814
	s_mov_b32 s6, 1
	s_mov_b64 s[8:9], 0
	s_branch .LBB0_1805

; DI unsigned xb_ld(unsigned* p)              { return __hip_atomic_load(p, __ATOMIC_RELAXED, __HIP_MEMORY_SCOPE_AGENT); }
; #define XB_SPIN(cond, bar) do { unsigned _sp = 0; while (cond) { __builtin_amdgcn_s_sleep(1); \
;     if ((++_sp & 255u) == 0u) { if (xb_ld(&(bar)[XB_TMO])) break; if (_sp > XB_SPIN_CAP) { atomicAdd(&(bar)[XB_TMO], 1u); break; } } } } while (0)
; DI void xcd_barrier(const XcdBarrier& b, int wid) {
;     ...
;         } else {
;             XB_SPIN(xb_ld(&bar[XB_XGEN(b.x)]) == gen, bar);
.Lxb_noearly_2:
	v_readlane_b32 s4, v255, 4
	v_readlane_b32 s5, v255, 5
	s_waitcnt lgkmcnt(0)
	s_nop 3
	global_load_dword v0, v97, s[4:5] sc1
	s_waitcnt vmcnt(0)
	v_cmp_eq_u32_e32 vcc, v0, v1
	s_and_saveexec_b64 s[4:5], vcc
	s_cbranch_execz .LBB0_2459
	s_mov_b32 s6, 1
	s_mov_b64 s[10:11], 0
	s_branch .LBB0_2450
